# same as previous (MoE weight conversion on 64 designated workgroups during attention) plus guards that fall back to the original path when the grid is not 256 workgroups
# speedup vs baseline: 1.0288x; 1.0016x over previous
; #define LAS __attribute__((address_space(3)))
; __device__ __forceinline__ int oi(int k) { asm volatile("" : "+s"(k)); return k; }
; #define opq(p) ((p) + oz())
; __device__ __forceinline__ const float* gfp(const float* p) { ASSUME_GLOBAL(p); return p; }
; #define ws opq(a.ws)
; __device__ __forceinline__ void cvt_moe(const Args& a, int ml, LAS float* scr, int gw, int NGW, int lane) {
;     asm volatile("" : "+v"(lane));
;     constexpr int I_GU = (DM / 64) * (2 * FFE / 32), I_D = (FFE / 64) * (DM / 32), I_E = I_GU + I_D;
;     const float* wg = gfp(a.in[oi(19)]) + (size_t)ml * NEXP * DM * FFE; const float* wu = gfp(a.in[oi(20)]) + (size_t)ml * NEXP * DM * FFE; const float* wd = gfp(a.in[oi(21)]) + (size_t)ml * NEXP * FFE * DM;
;     unsigned char* wsl = opq(a.ws); bf16_t* mgu = (bf16_t*)(wsl + WS_MGU); bf16_t* md = (bf16_t*)(wsl + WS_MD);
;     for (int it = gw; it < NEXP * I_E; it += NGW) {
;         const int e = it / I_E; int r = it % I_E;
;         if (r < I_GU) { MapGU f{wg + (size_t)e * DM * FFE, wu + (size_t)e * DM * FFE, FFE}; cvt_item<MapGU, true>(f, nullptr, DM, (bf16_t*)((unsigned char*)mgu + (size_t)e * 2 * FFE * DM), scr, r, 2 * FFE / 32, lane, W8_GU); }
;         else { r -= I_GU; MapPlain f{wd + (size_t)e * FFE * DM, DM}; cvt_item<MapPlain, true>(f, nullptr, FFE, (bf16_t*)((unsigned char*)md + (size_t)e * DM * FFE), scr, r, DM / 32, lane, W8_D); }
;     }
; }
.LBB0_90:
	v_mov_b32_e32 v1, v166
	v_readlane_b32 s72, v251, 6
	s_mov_b32 s26, s86
	s_cmp_gt_i32 s86, 0xa7ff
	s_mov_b32 s10, 19
	v_and_b32_e32 v2, 63, v1
	s_mov_b32 s8, 20
	s_mov_b32 s4, 21
	s_mov_b64 s[12:13], 0
	v_readlane_b32 s73, v251, 7
	s_cbranch_scc1 .LBB0_103
	s_cmpk_eq_i32 s94, 0x100
	s_cbranch_scc1 .LBB0_103
	s_ashr_i32 s11, s10, 31
	s_lshl_b64 s[10:11], s[10:11], 3
	s_add_u32 s16, s72, s10
	s_addc_u32 s17, s73, s11
	s_ashr_i32 s9, s8, 31
	s_lshl_b64 s[8:9], s[8:9], 3
	s_add_u32 s18, s72, s8
	s_addc_u32 s19, s73, s9
	s_ashr_i32 s5, s4, 31
	s_lshl_b64 s[4:5], s[4:5], 3
	s_add_u32 s20, s72, s4
	s_addc_u32 s21, s73, s5
	s_waitcnt lgkmcnt(0)
	s_add_u32 s12, s6, s12
	s_addc_u32 s14, s7, s13
	s_add_u32 s13, s12, 0x4400000
	s_load_dwordx2 s[4:5], s[16:17], 0x0
	s_load_dwordx2 s[8:9], s[18:19], 0x0
	s_load_dwordx2 s[10:11], s[20:21], 0x0
	s_addc_u32 s24, s14, 0
	s_mov_b32 s16, s26
	s_add_u32 s26, s12, 0xb400000
	v_lshlrev_b32_e32 v3, 2, v2
	s_addc_u32 s27, s14, 0
	v_ashrrev_i32_e32 v1, 3, v2
	v_and_b32_e32 v26, 28, v3
	v_readlane_b32 s14, v251, 5
	s_movk_i32 s12, 0x84
	v_lshlrev_b32_e32 v2, 3, v2
	v_lshl_add_u32 v10, v26, 2, s14
	v_mul_lo_u32 v11, v1, s12
	v_and_b32_e32 v4, 56, v2
	s_lshl_b32 s12, s16, 5
	v_mov_b32_e32 v3, 0
	v_mul_u32_u24_e32 v2, 0x84, v4
	v_lshlrev_b32_e32 v9, 2, v1
	s_add_i32 s28, s12, 0xfffe4000
	s_lshl_b32 s12, s16, 1
	v_add_u32_e32 v10, v10, v11
	v_add_u32_e32 v6, 8, v1
	v_add_u32_e32 v7, 16, v1
	v_add_u32_e32 v8, 24, v1
	v_mov_b32_e32 v5, v3
	v_add3_u32 v9, s14, v2, v9
	s_lshl_b32 s29, s94, 8
	s_add_i32 s30, s12, 0xffffe400
	s_lshl_b32 s31, s94, 4
	s_mov_b32 s34, 0x8000
	s_mov_b32 s35, 0x10000
	s_mov_b32 s36, 0x18000
	s_mov_b32 s37, 0x20000
	s_mov_b32 s38, 0x28000
	s_mov_b32 s39, 0x30000
	s_mov_b32 s40, 0x38000
	s_mov_b32 s12, 0x43000000
	v_add_u32_e32 v11, 0x420, v10
	v_add_u32_e32 v12, 0x428, v10
	v_add_u32_e32 v13, 0x840, v10
	v_add_u32_e32 v14, 0x848, v10
	v_add_u32_e32 v15, 0xc60, v10
	v_add_u32_e32 v16, 0xc68, v10
	v_add_u32_e32 v17, 0x1080, v10
	v_add_u32_e32 v18, 0x1088, v10
	v_add_u32_e32 v19, 0x14a0, v10
	v_add_u32_e32 v20, 0x14a8, v10
	v_add_u32_e32 v21, 0x18c0, v10
	v_add_u32_e32 v22, 0x18c8, v10
	v_add_u32_e32 v23, 0x1ce0, v10
	v_add_u32_e32 v24, 0x1ce8, v10
	s_movk_i32 s41, 0xe00
	s_movk_i32 s42, 0x3800
	s_mov_b32 s14, 0x42800000
	v_lshlrev_b32_e32 v2, 2, v26
	s_mov_b32 s43, s16
	s_branch .LBB0_94

; #define LAS __attribute__((address_space(3)))
; __device__ __forceinline__ int oi(int k) { asm volatile("" : "+s"(k)); return k; }
; #define opq(p) ((p) + oz())
; __device__ __forceinline__ const float* gfp(const float* p) { ASSUME_GLOBAL(p); return p; }
; #define ws opq(a.ws)
; __device__ __forceinline__ void cvt_moe(const Args& a, int ml, LAS float* scr, int gw, int NGW, int lane) {
;     asm volatile("" : "+v"(lane));
;     constexpr int I_GU = (DM / 64) * (2 * FFE / 32), I_D = (FFE / 64) * (DM / 32), I_E = I_GU + I_D;
;     const float* wg = gfp(a.in[oi(19)]) + (size_t)ml * NEXP * DM * FFE; const float* wu = gfp(a.in[oi(20)]) + (size_t)ml * NEXP * DM * FFE; const float* wd = gfp(a.in[oi(21)]) + (size_t)ml * NEXP * FFE * DM;
;     unsigned char* wsl = opq(a.ws); bf16_t* mgu = (bf16_t*)(wsl + WS_MGU); bf16_t* md = (bf16_t*)(wsl + WS_MD);
;     for (int it = gw; it < NEXP * I_E; it += NGW) {
;         const int e = it / I_E; int r = it % I_E;
;         if (r < I_GU) { MapGU f{wg + (size_t)e * DM * FFE, wu + (size_t)e * DM * FFE, FFE}; cvt_item<MapGU, true>(f, nullptr, DM, (bf16_t*)((unsigned char*)mgu + (size_t)e * 2 * FFE * DM), scr, r, 2 * FFE / 32, lane, W8_GU); }
;         else { r -= I_GU; MapPlain f{wd + (size_t)e * FFE * DM, DM}; cvt_item<MapPlain, true>(f, nullptr, FFE, (bf16_t*)((unsigned char*)md + (size_t)e * DM * FFE), scr, r, DM / 32, lane, W8_D); }
;     }
; }
.Lcve_go:
	v_readlane_b32 s101, v251, 2
	s_nop 3
	s_and_b32 s100, s101, 3
	s_cmp_eq_u32 s100, 0
	s_cbranch_scc0 .Lcve_done
	v_writelane_b32 v145, s8, 0
	v_writelane_b32 v145, s9, 1
	v_writelane_b32 v145, s10, 2
	v_writelane_b32 v145, s11, 3
	v_writelane_b32 v145, s12, 4
	v_writelane_b32 v145, s13, 5
	v_writelane_b32 v145, s14, 6
	v_writelane_b32 v145, s15, 7
	v_writelane_b32 v145, s16, 8
	v_writelane_b32 v145, s17, 9
	v_writelane_b32 v145, s18, 10
	v_writelane_b32 v145, s19, 11
	v_writelane_b32 v145, s20, 12
	v_writelane_b32 v145, s21, 13
	v_writelane_b32 v145, s22, 14
	v_writelane_b32 v145, s23, 15
	v_writelane_b32 v145, s24, 16
	v_writelane_b32 v145, s25, 17
	v_writelane_b32 v145, s26, 18
	v_writelane_b32 v145, s27, 19
	v_writelane_b32 v145, s28, 20
	v_writelane_b32 v145, s29, 21
	v_writelane_b32 v145, s30, 22
	v_writelane_b32 v145, s31, 23
	v_writelane_b32 v145, s32, 24
	v_writelane_b32 v145, s33, 25
	v_writelane_b32 v145, s34, 26
	v_writelane_b32 v145, s35, 27
	v_writelane_b32 v145, s36, 28
	v_writelane_b32 v145, s37, 29
	v_writelane_b32 v145, s38, 30
	v_writelane_b32 v145, s39, 31
	v_writelane_b32 v145, s40, 32
	v_writelane_b32 v145, s41, 33
	v_writelane_b32 v145, s42, 34
	v_writelane_b32 v145, s43, 35
	v_writelane_b32 v145, s44, 36
	v_writelane_b32 v145, s45, 37
	v_writelane_b32 v145, s46, 38
	v_writelane_b32 v145, s47, 39
	s_mov_b64 s[8:9], exec
	s_mov_b64 exec, -1
	v_readlane_b32 s10, v251, 6
	v_readlane_b32 s11, v251, 7
	s_nop 3
	s_load_dwordx2 s[12:13], s[10:11], 0x98
	s_load_dwordx2 s[14:15], s[10:11], 0xa0
	s_load_dwordx2 s[16:17], s[10:11], 0xa8
	s_load_dwordx2 s[18:19], s[10:11], 0xb8
	s_load_dword s45, s[10:11], 0x218
	s_waitcnt lgkmcnt(0)
	s_cmpk_lg_i32 s45, 0x100
	s_cbranch_scc1 .Lcve_fin
	v_and_b32_e32 v5, 63, v166
	v_lshrrev_b32_e32 v6, 3, v5
	v_and_b32_e32 v7, 7, v5
	v_lshlrev_b32_e32 v10, 3, v7
	v_readfirstlane_b32 s46, v166
	v_mul_u32_u24_e32 v8, 0x84, v6
	v_mul_u32_u24_e32 v9, 0x420, v7
	v_lshlrev_b32_e32 v7, 4, v7
	s_lshr_b32 s46, s46, 6
	s_lshl_b32 s47, s46, 14
	v_add3_u32 v8, v8, v7, s47
	v_lshl_add_u32 v9, v6, 2, v9
	v_add_u32_e32 v9, s47, v9
	v_add_u32_e32 v128, 0, v8
	v_add_u32_e32 v129, 1056, v8
	v_add_u32_e32 v130, 2112, v8
	v_add_u32_e32 v131, 3168, v8
	v_add_u32_e32 v132, 4224, v8
	v_add_u32_e32 v133, 5280, v8
	v_add_u32_e32 v134, 6336, v8
	v_add_u32_e32 v135, 7392, v8
	s_movk_i32 s41, 0x3800
	v_mad_u32_u24 v11, v6, s41, v7
	v_add_u32_e32 v12, 0x1c000, v11
	v_add_u32_e32 v13, 0x1c000, v12
	v_add_u32_e32 v14, 0x1c000, v13
	v_add_u32_e32 v15, 0x1c000, v14
	v_add_u32_e32 v16, 0x1c000, v15
	v_add_u32_e32 v17, 0x1c000, v16
	v_add_u32_e32 v18, 0x1c000, v17
	s_movk_i32 s41, 0x1000
	v_mad_u32_u24 v136, v6, s41, v7
	v_add_u32_e32 v137, 0x8000, v136
	v_add_u32_e32 v138, 0x8000, v137
	v_add_u32_e32 v139, 0x8000, v138
	v_add_u32_e32 v140, 0x8000, v139
	v_add_u32_e32 v141, 0x8000, v140
	v_add_u32_e32 v142, 0x8000, v141
	v_add_u32_e32 v143, 0x8000, v142
	v_lshl_add_u32 v19, v6, 10, v10
	v_add_u32_e32 v20, 0x2000, v19
	v_add_u32_e32 v21, 0x2000, v20
	v_add_u32_e32 v22, 0x2000, v21
	s_movk_i32 s41, 0xe00
	v_mad_u32_u24 v144, v6, s41, v10
	v_add_u32_e32 v23, 0x7000, v144
	v_add_u32_e32 v5, 0x7000, v23
	v_add_u32_e32 v7, 0x7000, v5
	s_lshr_b32 s42, s101, 2
	s_lshl_b32 s42, s42, 3
	s_add_u32 s20, s42, s46
	s_movk_i32 s21, 84
	s_mov_b32 s22, s20
	s_lshr_b32 s41, s90, 1
	s_mul_i32 s41, s41, 0x7000000
	s_waitcnt lgkmcnt(0)
	s_add_u32 s12, s12, s41
	s_addc_u32 s13, s13, 0
	s_add_u32 s14, s14, s41
	s_addc_u32 s15, s15, 0
	s_add_u32 s16, s16, s41
	s_addc_u32 s17, s17, 0

; __device__ __forceinline__ int fresh_lane() { int t = threadIdx.x; asm volatile("" : "+v"(t)); return t & 63; }
; __device__ __forceinline__ int oi(int k) { asm volatile("" : "+s"(k)); return k; }
; __device__ __forceinline__ const float* gfp(const float* p) { ASSUME_GLOBAL(p); return p; }
; #define ws opq(a.ws)
; #define PH_BEGIN(k) if (lo <= ph && ph < hi) { if constexpr ((EN >> (k)) & 1) for (int rep_ = 0; rep_ < ((((REP) >> (k)) & 1) ? 2 : 1); ++rep_) {
; #define PH_END() } if (ph + 1 < hi) { if (ph == 0) grid.sync(); else xcd_barrier(xbar); } } ++ph;
; __global__ void __launch_bounds__(512, 2) mega_fwd(Args a) {
;     ...
;         PH_BEGIN(5)
;         { if (moe) ln_pass<0, true, true, true>(a, Y, nullptr, gfp(a.in[oi(11)]) + l * DM, gfp(a.in[oi(12)]) + l * DM, Xf, (bf16_t*)(ws + WS_XB8), gfp(a.in[oi(18)]) + (size_t)li * DM * 8, ctl + CW_CNT + 8 * li, gw, NGW, fresh_lane(), lds);
;           else ln_pass<0, false, true, true>(a, Y, nullptr, gfp(a.in[oi(11)]) + l * DM, gfp(a.in[oi(12)]) + l * DM, Xf, (bf16_t*)(ws + WS_XB8), nullptr, nullptr, gw, NGW, fresh_lane(), lds);
;           if (l == 2) cvt_moe(a, 1, scr, gw, NGW, fresh_lane()); }
;         PH_END()
.LBB0_1078:
	s_cmp_lg_u32 s90, 2
	s_cbranch_scc1 .LBB0_1090
	v_readlane_b32 s10, v251, 6
	v_readlane_b32 s11, v251, 7
	s_nop 3
	s_load_dword s8, s[10:11], 0x218
	s_waitcnt lgkmcnt(0)
	s_cmpk_eq_i32 s8, 0x100
	s_cbranch_scc1 .LBB0_1090
	v_mov_b32_e32 v0, v166
	v_readlane_b32 s10, v252, 26
	v_readlane_b32 s11, v252, 27
	v_and_b32_e32 v0, 63, v0
	s_mov_b32 s8, 19
	s_mov_b32 s6, 20
	s_mov_b32 s2, 21
	s_mov_b64 s[4:5], 0
	s_andn2_b64 vcc, exec, s[10:11]
	s_cbranch_vccnz .LBB0_1090
	s_ashr_i32 s9, s8, 31
	s_lshl_b64 s[8:9], s[8:9], 3
	s_add_u32 s8, s72, s8
	s_addc_u32 s9, s73, s9
	s_load_dwordx2 s[8:9], s[8:9], 0x0
	v_ashrrev_i32_e32 v3, 3, v0
	v_lshlrev_b32_e32 v2, 2, v0
	v_lshlrev_b32_e32 v0, 3, v0
	v_and_b32_e32 v2, 28, v2
	s_waitcnt lgkmcnt(0)
	s_add_u32 s16, s8, 0x7000000
	s_addc_u32 s17, s9, 0
	s_ashr_i32 s7, s6, 31
	s_lshl_b64 s[6:7], s[6:7], 3
	s_add_u32 s6, s72, s6
	s_addc_u32 s7, s73, s7
	s_ashr_i32 s3, s2, 31
	s_lshl_b64 s[2:3], s[2:3], 3
	s_add_u32 s8, s72, s2
	s_addc_u32 s9, s73, s3
	s_load_dwordx2 s[2:3], s[6:7], 0x0
	s_nop 0
	s_load_dwordx2 s[6:7], s[8:9], 0x0
	s_movk_i32 s8, 0x84
	v_mul_lo_u32 v6, v3, s8
	v_readlane_b32 s8, v251, 5
	v_and_b32_e32 v4, 56, v0
	s_waitcnt lgkmcnt(0)
	s_add_u32 s18, s6, 0x7000000
	s_addc_u32 s19, s7, 0
	s_add_u32 s4, s14, s4
	s_addc_u32 s5, s15, s5
	s_add_u32 s24, s4, 0x4400000
	s_addc_u32 s25, s5, 0
	s_add_u32 s26, s4, 0xb400000
	s_addc_u32 s28, s5, 0
	v_readlane_b32 s4, v254, 2
	s_mov_b32 s6, s4
	s_lshl_b32 s4, s4, 5
	v_lshl_add_u32 v7, v2, 2, s8
	v_mul_u32_u24_e32 v0, 0x84, v4
	v_lshlrev_b32_e32 v8, 2, v3
	s_add_i32 s29, s4, 0xfffe4000
	s_lshl_b32 s4, s6, 1
	v_add_u32_e32 v16, 8, v3
	v_add_u32_e32 v17, 16, v3
	v_add_u32_e32 v18, 24, v3
	v_mov_b32_e32 v5, v1
	v_add3_u32 v19, s8, v0, v8
	s_add_i32 s30, s4, 0xffffe400
	v_add_u32_e32 v20, v7, v6
	s_mov_b32 s31, s6
	v_readlane_b32 s5, v254, 3
	s_branch .LBB0_1083
